# static s_setprio on the LIVE P8 K loop (.LBB0_1317, the G==256 instance): per-phase flips removed, waves 0-3 raised once before the loop
# speedup vs baseline: 1.0052x; 1.0052x over previous
; #define PG8_STAGE(bufoff, gbase, voff) do { _Pragma("unroll") for (int _i = 0; _i < 2; ++_i) \
;         __builtin_amdgcn_global_load_lds((const unsigned*)((const char*)(gbase) + (voff)[_i]), (LAS unsigned*)(lds + (bufoff) + ldsw + _i * 8192), 16, 0, 0); } while (0)
; #define PG8_LDA(dst, b, h) do { _Pragma("unroll") for (int m = 0; m < 4; ++m) _Pragma("unroll") for (int k = 0; k < 2; ++k) dst[m][k] = *(const LAS bf16x8*)(lds + PG8_SA(b, h) + aoff + m * 2048 + k * 1024); } while (0)
; #define PG8_LDB(dst, b, h) do { _Pragma("unroll") for (int n = 0; n < 2; ++n) _Pragma("unroll") for (int k = 0; k < 2; ++k) dst[n][k] = *(const LAS bf16x8*)(lds + PG8_SB(b, h) + boff + n * 2048 + k * 1024); } while (0)
; #define PG8_WAIT_V(n) asm volatile("s_waitcnt vmcnt(" #n ")" ::: "memory")
; #define PG8_WAIT_L(n) asm volatile("s_waitcnt lgkmcnt(" #n ")" ::: "memory")
; #define PG8_BAR __builtin_amdgcn_s_barrier()
; template <class Epi, class Sched>
; __device__ __forceinline__ void gemm_phase(LAS unsigned char* lds, const Gemm g, const Sched& S, const Epi& E) {
;     ...
;     for (;;) {
;         const bool has_next = S.next(ui + 1, nxt);
;         const char* nA = has_next ? (const char*)g.A + (size_t)nxt.pm * tstepA + (size_t)nxt.koffA * 2 : cA; const char* nB = has_next ? (const char*)g.Bt + (size_t)nxt.pn * tstepB + (size_t)nxt.koffB * 2 : cB;
; #pragma clang loop unroll(disable)
;         for (int t = 0; t < nt; t += 2) {
;             const bool last = (t == nt - 2);
;             const char* a1 = cA + (size_t)(t + 1) * kstep;
;             const char* a2 = last ? nA : cA + (size_t)(t + 2) * kstep; const char* b2 = last ? nB : cB + (size_t)(t + 2) * kstep;
;             const char* a3 = a2 + kstep; const char* b3 = b2 + kstep;
;             PG8_LDB(B0, 0, 0); PG8_SCHED; PG8_LDA(At, 0, 0); PG8_STAGE(PG8_SA(1, 1), a1 + hstepA, voffA);
;             PG8_WAIT_L(8); PG8_BAR; PG8_WAIT_L(0); PG8_MMA(0, 0, At, B0); PG8_BAR; PG8_SCHED;
;             PG8_LDB(B1, 0, 1); PG8_STAGE(PG8_SB(0, 0), b2, voffB);
;             PG8_BAR; PG8_WAIT_L(0); PG8_MMA(0, 1, At, B1); PG8_BAR;
;             PG8_LDA(At, 0, 1); PG8_STAGE(PG8_SA(0, 0), a2, voffA);
;             PG8_BAR; PG8_WAIT_L(0); PG8_MMA(1, 0, At, B0); PG8_BAR; PG8_SCHED;
;             PG8_STAGE(PG8_SB(0, 1), b2 + hstepB, voffB);
;             PG8_WAIT_V(6); PG8_BAR; PG8_MMA(1, 1, At, B1); PG8_BAR;
.LBB0_1316:
	s_add_u32 s4, s20, 0x100
	s_addc_u32 s5, s21, 0
	v_lshl_add_u64 v[140:141], s[10:11], 0, v[132:133]
	v_lshl_add_u64 v[142:143], s[10:11], 0, v[134:135]
	s_mov_b32 s17, -2
	s_mov_b64 s[20:21], 0
	v_readfirstlane_b32 vcc_lo, v196
	s_nop 3
	s_lshr_b32 vcc_lo, vcc_lo, 8
	s_cmp_lg_u32 vcc_lo, 0
	s_cbranch_scc1 .Lp8b_prio_done
	s_setprio 1
.Lp8b_prio_done:
.LBB0_1317:
	v_add_u32_e32 v158, s40, v144
	s_add_u32 s24, s10, s20
	ds_read_b128 v[146:149], v158
	ds_read_b128 v[150:153], v158 offset:1024
	ds_read_b128 v[154:157], v158 offset:2048
	ds_read_b128 v[158:161], v158 offset:3072
	s_addc_u32 s25, s11, s21
	s_add_u32 s24, s24, 0x100
	s_addc_u32 s25, s25, 0
	s_add_u32 s44, s4, s20
	s_addc_u32 s45, s5, s21
	s_cmpk_eq_i32 s20, 0x2b00
	s_cselect_b32 s27, s19, s25
	s_cselect_b32 s26, s18, s24
	s_cselect_b32 s25, s9, s45
	s_cselect_b32 s24, s8, s44
	v_lshl_add_u64 v[178:179], v[140:141], 0, s[20:21]
	s_add_i32 m0, s29, 0xc000
	ds_read_b128 v[162:165], v145
	ds_read_b128 v[166:169], v145 offset:1024
	ds_read_b128 v[170:173], v145 offset:2048
	ds_read_b128 v[174:177], v145 offset:3072
	ds_read_b128 v[190:193], v145 offset:4096
	ds_read_b128 v[198:201], v145 offset:5120
	ds_read_b128 v[202:205], v145 offset:6144
	ds_read_b128 v[206:209], v145 offset:7168
	global_load_lds_dwordx4 v[178:179], off
	v_lshl_add_u64 v[178:179], v[142:143], 0, s[20:21]
	s_add_i32 m0, s29, 0xe000
	s_nop 0
	global_load_lds_dwordx4 v[178:179], off
	s_waitcnt lgkmcnt(8)
	s_barrier
	s_waitcnt lgkmcnt(0)
	s_waitcnt lgkmcnt(0)
	v_mfma_f32_16x16x32_bf16 v[124:127], v[146:149], v[162:165], v[124:127]
	v_mfma_f32_16x16x32_bf16 v[120:123], v[154:157], v[162:165], v[120:123]
	v_mfma_f32_16x16x32_bf16 v[108:111], v[146:149], v[170:173], v[108:111]
	v_mfma_f32_16x16x32_bf16 v[104:107], v[154:157], v[170:173], v[104:107]
	v_mfma_f32_16x16x32_bf16 v[92:95], v[146:149], v[190:193], v[92:95]
	v_mfma_f32_16x16x32_bf16 v[88:91], v[154:157], v[190:193], v[88:91]
	v_mfma_f32_16x16x32_bf16 v[76:79], v[146:149], v[202:205], v[76:79]
	v_mfma_f32_16x16x32_bf16 v[72:75], v[154:157], v[202:205], v[72:75]
	v_mfma_f32_16x16x32_bf16 v[124:127], v[150:153], v[166:169], v[124:127]
	v_mfma_f32_16x16x32_bf16 v[120:123], v[158:161], v[166:169], v[120:123]
	v_mfma_f32_16x16x32_bf16 v[108:111], v[150:153], v[174:177], v[108:111]
	v_mfma_f32_16x16x32_bf16 v[104:107], v[158:161], v[174:177], v[104:107]
	v_mfma_f32_16x16x32_bf16 v[92:95], v[150:153], v[198:201], v[92:95]
	v_mfma_f32_16x16x32_bf16 v[88:91], v[158:161], v[198:201], v[88:91]
	v_mfma_f32_16x16x32_bf16 v[76:79], v[150:153], v[206:209], v[76:79]
	v_mfma_f32_16x16x32_bf16 v[72:75], v[158:161], v[206:209], v[72:75]
	s_barrier
	v_add_u32_e32 v178, s41, v144
	s_add_i32 s44, s40, s23
	ds_read_b128 v[210:213], v178
	ds_read_b128 v[214:217], v178 offset:1024
	ds_read_b128 v[218:221], v178 offset:2048
	ds_read_b128 v[222:225], v178 offset:3072
	v_lshl_add_u64 v[178:179], s[24:25], 0, v[128:129]
	s_mov_b32 m0, s44
	v_lshl_add_u64 v[194:195], s[24:25], 0, v[130:131]
	global_load_lds_dwordx4 v[178:179], off
	s_add_i32 m0, s44, 0x2000
	s_nop 0
	global_load_lds_dwordx4 v[194:195], off
	s_barrier
	s_waitcnt lgkmcnt(0)
	s_waitcnt lgkmcnt(0)
	v_mfma_f32_16x16x32_bf16 v[116:119], v[210:213], v[162:165], v[116:119]
	v_mfma_f32_16x16x32_bf16 v[112:115], v[218:221], v[162:165], v[112:115]
	v_mfma_f32_16x16x32_bf16 v[100:103], v[210:213], v[170:173], v[100:103]
	v_mfma_f32_16x16x32_bf16 v[96:99], v[218:221], v[170:173], v[96:99]
	v_mfma_f32_16x16x32_bf16 v[84:87], v[210:213], v[190:193], v[84:87]
	v_mfma_f32_16x16x32_bf16 v[80:83], v[218:221], v[190:193], v[80:83]
	v_mfma_f32_16x16x32_bf16 v[68:71], v[210:213], v[202:205], v[68:71]
	v_mfma_f32_16x16x32_bf16 v[64:67], v[218:221], v[202:205], v[64:67]
	v_mfma_f32_16x16x32_bf16 v[116:119], v[214:217], v[166:169], v[116:119]
	v_mfma_f32_16x16x32_bf16 v[112:115], v[222:225], v[166:169], v[112:115]
	v_mfma_f32_16x16x32_bf16 v[100:103], v[214:217], v[174:177], v[100:103]
	v_mfma_f32_16x16x32_bf16 v[96:99], v[222:225], v[174:177], v[96:99]
	v_mfma_f32_16x16x32_bf16 v[84:87], v[214:217], v[198:201], v[84:87]
	v_mfma_f32_16x16x32_bf16 v[80:83], v[222:225], v[198:201], v[80:83]
	v_mfma_f32_16x16x32_bf16 v[68:71], v[214:217], v[206:209], v[68:71]
	v_mfma_f32_16x16x32_bf16 v[64:67], v[222:225], v[206:209], v[64:67]
	s_mov_b32 m0, s29
	v_lshl_add_u64 v[226:227], s[26:27], 0, v[128:129]
	s_barrier
	ds_read_b128 v[162:165], v145 offset:16384
	ds_read_b128 v[166:169], v145 offset:17408
	ds_read_b128 v[170:173], v145 offset:18432
	ds_read_b128 v[174:177], v145 offset:19456
	ds_read_b128 v[190:193], v145 offset:20480
	ds_read_b128 v[198:201], v145 offset:21504
	ds_read_b128 v[202:205], v145 offset:22528
	ds_read_b128 v[206:209], v145 offset:23552
	global_load_lds_dwordx4 v[226:227], off
	v_lshl_add_u64 v[228:229], s[26:27], 0, v[130:131]
	s_mov_b32 m0, s30
	s_nop 0
	global_load_lds_dwordx4 v[228:229], off
	s_barrier
	s_waitcnt lgkmcnt(0)
	s_waitcnt lgkmcnt(0)
	v_mfma_f32_16x16x32_bf16 v[60:63], v[146:149], v[162:165], v[60:63]
	v_mfma_f32_16x16x32_bf16 v[56:59], v[154:157], v[162:165], v[56:59]
	v_mfma_f32_16x16x32_bf16 v[44:47], v[146:149], v[170:173], v[44:47]
	v_mfma_f32_16x16x32_bf16 v[40:43], v[154:157], v[170:173], v[40:43]
	v_mfma_f32_16x16x32_bf16 v[28:31], v[146:149], v[190:193], v[28:31]
	v_mfma_f32_16x16x32_bf16 v[24:27], v[154:157], v[190:193], v[24:27]
	v_mfma_f32_16x16x32_bf16 v[16:19], v[146:149], v[202:205], v[16:19]
	v_mfma_f32_16x16x32_bf16 v[8:11], v[154:157], v[202:205], v[8:11]
	v_mfma_f32_16x16x32_bf16 v[60:63], v[150:153], v[166:169], v[60:63]
	v_mfma_f32_16x16x32_bf16 v[56:59], v[158:161], v[166:169], v[56:59]
	v_mfma_f32_16x16x32_bf16 v[44:47], v[150:153], v[174:177], v[44:47]
	v_mfma_f32_16x16x32_bf16 v[40:43], v[158:161], v[174:177], v[40:43]
	v_mfma_f32_16x16x32_bf16 v[28:31], v[150:153], v[198:201], v[28:31]
	v_mfma_f32_16x16x32_bf16 v[24:27], v[158:161], v[198:201], v[24:27]
	v_mfma_f32_16x16x32_bf16 v[16:19], v[150:153], v[206:209], v[16:19]
	v_mfma_f32_16x16x32_bf16 v[8:11], v[158:161], v[206:209], v[8:11]
	s_barrier
; #define PG8_STAGE(bufoff, gbase, voff) do { _Pragma("unroll") for (int _i = 0; _i < 2; ++_i) \
;         __builtin_amdgcn_global_load_lds((const unsigned*)((const char*)(gbase) + (voff)[_i]), (LAS unsigned*)(lds + (bufoff) + ldsw + _i * 8192), 16, 0, 0); } while (0)
; #define PG8_LDA(dst, b, h) do { _Pragma("unroll") for (int m = 0; m < 4; ++m) _Pragma("unroll") for (int k = 0; k < 2; ++k) dst[m][k] = *(const LAS bf16x8*)(lds + PG8_SA(b, h) + aoff + m * 2048 + k * 1024); } while (0)
; #define PG8_LDB(dst, b, h) do { _Pragma("unroll") for (int n = 0; n < 2; ++n) _Pragma("unroll") for (int k = 0; k < 2; ++k) dst[n][k] = *(const LAS bf16x8*)(lds + PG8_SB(b, h) + boff + n * 2048 + k * 1024); } while (0)
; #define PG8_MMA(ai, bj, At, Bt) do { __builtin_amdgcn_s_setprio(1); _Pragma("unroll") for (int m = 0; m < 4; ++m) _Pragma("unroll") for (int n = 0; n < 2; ++n) _Pragma("unroll") for (int k = 0; k < 2; ++k) \
;         acc[ai][bj][m][n] = __builtin_amdgcn_mfma_f32_16x16x32_bf16(Bt[n][k], At[m][k], acc[ai][bj][m][n], 0, 0, 0); __builtin_amdgcn_s_setprio(0); } while (0)
; #define PG8_WAIT_V(n) asm volatile("s_waitcnt vmcnt(" #n ")" ::: "memory")
; #define PG8_WAIT_L(n) asm volatile("s_waitcnt lgkmcnt(" #n ")" ::: "memory")
; #define PG8_BAR __builtin_amdgcn_s_barrier()
; #define PG8_SCHED __builtin_amdgcn_sched_barrier(0)
; template <class Epi, class Sched>
; __device__ __forceinline__ void gemm_phase(LAS unsigned char* lds, const Gemm g, const Sched& S, const Epi& E) {
;     ...
;             PG8_STAGE(PG8_SB(0, 1), b2 + hstepB, voffB);
;             PG8_WAIT_V(6); PG8_BAR; PG8_MMA(1, 1, At, B1); PG8_BAR;
;             PG8_LDB(B0, 1, 0); PG8_SCHED; PG8_LDA(At, 1, 0); PG8_STAGE(PG8_SA(0, 1), a2 + hstepA, voffA);
;             PG8_WAIT_L(8); PG8_BAR; PG8_WAIT_L(0); PG8_MMA(0, 0, At, B0); PG8_BAR; PG8_SCHED;
;             PG8_LDB(B1, 1, 1); PG8_STAGE(PG8_SB(1, 0), b3, voffB);
;             PG8_BAR; PG8_WAIT_L(0); PG8_MMA(0, 1, At, B1); PG8_BAR;
;             PG8_LDA(At, 1, 1); PG8_STAGE(PG8_SA(1, 0), a3, voffA);
;             PG8_BAR; PG8_WAIT_L(0); PG8_MMA(1, 0, At, B0); PG8_BAR; PG8_SCHED;
;             PG8_STAGE(PG8_SB(1, 1), b3 + hstepB, voffB);
	s_add_u32 s44, s24, 0x160000
	s_addc_u32 s45, s25, 0
	s_add_i32 s50, s41, s23
	v_lshl_add_u64 v[146:147], s[44:45], 0, v[128:129]
	s_mov_b32 m0, s50
	s_nop 0
	global_load_lds_dwordx4 v[146:147], off
	v_lshl_add_u64 v[146:147], s[44:45], 0, v[130:131]
	s_add_i32 m0, s50, 0x2000
	s_nop 0
	global_load_lds_dwordx4 v[146:147], off
	s_waitcnt vmcnt(6)
	s_barrier
	v_mfma_f32_16x16x32_bf16 v[52:55], v[210:213], v[162:165], v[52:55]
	v_mfma_f32_16x16x32_bf16 v[48:51], v[218:221], v[162:165], v[48:51]
	v_mfma_f32_16x16x32_bf16 v[36:39], v[210:213], v[170:173], v[36:39]
	v_mfma_f32_16x16x32_bf16 v[32:35], v[218:221], v[170:173], v[32:35]
	v_mfma_f32_16x16x32_bf16 v[20:23], v[210:213], v[190:193], v[20:23]
	v_mfma_f32_16x16x32_bf16 v[12:15], v[218:221], v[190:193], v[12:15]
	v_mfma_f32_16x16x32_bf16 v[4:7], v[210:213], v[202:205], v[4:7]
	v_mfma_f32_16x16x32_bf16 v[0:3], v[218:221], v[202:205], v[0:3]
	v_mfma_f32_16x16x32_bf16 v[52:55], v[214:217], v[166:169], v[52:55]
	v_mfma_f32_16x16x32_bf16 v[48:51], v[222:225], v[166:169], v[48:51]
	v_mfma_f32_16x16x32_bf16 v[36:39], v[214:217], v[174:177], v[36:39]
	v_mfma_f32_16x16x32_bf16 v[32:35], v[222:225], v[174:177], v[32:35]
	v_mfma_f32_16x16x32_bf16 v[20:23], v[214:217], v[198:201], v[20:23]
	v_mfma_f32_16x16x32_bf16 v[12:15], v[222:225], v[198:201], v[12:15]
	v_mfma_f32_16x16x32_bf16 v[4:7], v[214:217], v[206:209], v[4:7]
	v_mfma_f32_16x16x32_bf16 v[0:3], v[222:225], v[206:209], v[0:3]
	s_add_i32 s44, 0, 0x18000
	v_add_u32_e32 v158, s44, v144
	s_barrier
	ds_read_b128 v[146:149], v158
	ds_read_b128 v[150:153], v158 offset:1024
	ds_read_b128 v[154:157], v158 offset:2048
	ds_read_b128 v[158:161], v158 offset:3072
	s_add_u32 s26, s26, 0x160000
	s_addc_u32 s27, s27, 0
	s_mov_b32 m0, s31
	v_lshl_add_u64 v[210:211], s[26:27], 0, v[128:129]
	ds_read_b128 v[162:165], v145 offset:32768
	ds_read_b128 v[166:169], v145 offset:33792
	ds_read_b128 v[170:173], v145 offset:34816
	ds_read_b128 v[174:177], v145 offset:35840
	ds_read_b128 v[190:193], v145 offset:36864
	ds_read_b128 v[198:201], v145 offset:37888
	ds_read_b128 v[202:205], v145 offset:38912
	ds_read_b128 v[206:209], v145 offset:39936
	global_load_lds_dwordx4 v[210:211], off
	v_lshl_add_u64 v[210:211], s[26:27], 0, v[130:131]
	s_mov_b32 m0, s33
	s_nop 0
	global_load_lds_dwordx4 v[210:211], off
	s_waitcnt lgkmcnt(8)
	s_barrier
	s_waitcnt lgkmcnt(0)
	s_waitcnt lgkmcnt(0)
	v_mfma_f32_16x16x32_bf16 v[124:127], v[146:149], v[162:165], v[124:127]
	v_mfma_f32_16x16x32_bf16 v[120:123], v[154:157], v[162:165], v[120:123]
	v_mfma_f32_16x16x32_bf16 v[108:111], v[146:149], v[170:173], v[108:111]
	v_mfma_f32_16x16x32_bf16 v[104:107], v[154:157], v[170:173], v[104:107]
	v_mfma_f32_16x16x32_bf16 v[92:95], v[146:149], v[190:193], v[92:95]
	v_mfma_f32_16x16x32_bf16 v[88:91], v[154:157], v[190:193], v[88:91]
	v_mfma_f32_16x16x32_bf16 v[76:79], v[146:149], v[202:205], v[76:79]
	v_mfma_f32_16x16x32_bf16 v[72:75], v[154:157], v[202:205], v[72:75]
	v_mfma_f32_16x16x32_bf16 v[124:127], v[150:153], v[166:169], v[124:127]
	v_mfma_f32_16x16x32_bf16 v[120:123], v[158:161], v[166:169], v[120:123]
	v_mfma_f32_16x16x32_bf16 v[108:111], v[150:153], v[174:177], v[108:111]
	v_mfma_f32_16x16x32_bf16 v[104:107], v[158:161], v[174:177], v[104:107]
	v_mfma_f32_16x16x32_bf16 v[92:95], v[150:153], v[198:201], v[92:95]
	v_mfma_f32_16x16x32_bf16 v[88:91], v[158:161], v[198:201], v[88:91]
	v_mfma_f32_16x16x32_bf16 v[76:79], v[150:153], v[206:209], v[76:79]
	v_mfma_f32_16x16x32_bf16 v[72:75], v[158:161], v[206:209], v[72:75]
	s_barrier
	s_add_i32 s26, 0, 0x1c000
	s_add_i32 s27, s44, s23
	v_add_u32_e32 v189, s26, v144
	v_lshl_add_u64 v[178:179], v[178:179], 0, s[12:13]
	s_mov_b32 m0, s27
	ds_read_b128 v[210:213], v189
	ds_read_b128 v[214:217], v189 offset:1024
	ds_read_b128 v[218:221], v189 offset:2048
	ds_read_b128 v[222:225], v189 offset:3072
	global_load_lds_dwordx4 v[178:179], off
	v_lshl_add_u64 v[178:179], v[194:195], 0, s[12:13]
	s_add_i32 m0, s27, 0x2000
	s_nop 0
	global_load_lds_dwordx4 v[178:179], off
	s_barrier
	s_waitcnt lgkmcnt(0)
	s_waitcnt lgkmcnt(0)
	v_mfma_f32_16x16x32_bf16 v[116:119], v[210:213], v[162:165], v[116:119]
	v_mfma_f32_16x16x32_bf16 v[112:115], v[218:221], v[162:165], v[112:115]
	v_mfma_f32_16x16x32_bf16 v[100:103], v[210:213], v[170:173], v[100:103]
	v_mfma_f32_16x16x32_bf16 v[96:99], v[218:221], v[170:173], v[96:99]
	v_mfma_f32_16x16x32_bf16 v[84:87], v[210:213], v[190:193], v[84:87]
	v_mfma_f32_16x16x32_bf16 v[80:83], v[218:221], v[190:193], v[80:83]
	v_mfma_f32_16x16x32_bf16 v[68:71], v[210:213], v[202:205], v[68:71]
	v_mfma_f32_16x16x32_bf16 v[64:67], v[218:221], v[202:205], v[64:67]
	v_mfma_f32_16x16x32_bf16 v[116:119], v[214:217], v[166:169], v[116:119]
	v_mfma_f32_16x16x32_bf16 v[112:115], v[222:225], v[166:169], v[112:115]
	v_mfma_f32_16x16x32_bf16 v[100:103], v[214:217], v[174:177], v[100:103]
	v_mfma_f32_16x16x32_bf16 v[96:99], v[222:225], v[174:177], v[96:99]
	v_mfma_f32_16x16x32_bf16 v[84:87], v[214:217], v[198:201], v[84:87]
	v_mfma_f32_16x16x32_bf16 v[80:83], v[222:225], v[198:201], v[80:83]
	v_mfma_f32_16x16x32_bf16 v[68:71], v[214:217], v[206:209], v[68:71]
	v_mfma_f32_16x16x32_bf16 v[64:67], v[222:225], v[206:209], v[64:67]
	s_mov_b32 m0, s36
	v_lshl_add_u64 v[178:179], v[226:227], 0, s[12:13]
	s_barrier
	ds_read_b128 v[162:165], v145 offset:49152
	ds_read_b128 v[166:169], v145 offset:50176
	ds_read_b128 v[170:173], v145 offset:51200
	ds_read_b128 v[174:177], v145 offset:52224
	ds_read_b128 v[190:193], v145 offset:53248
	ds_read_b128 v[198:201], v145 offset:54272
	ds_read_b128 v[202:205], v145 offset:55296
	ds_read_b128 v[206:209], v145 offset:56320
	global_load_lds_dwordx4 v[178:179], off
	v_lshl_add_u64 v[178:179], v[228:229], 0, s[12:13]
	s_mov_b32 m0, s37
	s_nop 0
	global_load_lds_dwordx4 v[178:179], off
	s_barrier
; #define PG8_STAGE(bufoff, gbase, voff) do { _Pragma("unroll") for (int _i = 0; _i < 2; ++_i) \
;         __builtin_amdgcn_global_load_lds((const unsigned*)((const char*)(gbase) + (voff)[_i]), (LAS unsigned*)(lds + (bufoff) + ldsw + _i * 8192), 16, 0, 0); } while (0)
; #define PG8_MMA(ai, bj, At, Bt) do { __builtin_amdgcn_s_setprio(1); _Pragma("unroll") for (int m = 0; m < 4; ++m) _Pragma("unroll") for (int n = 0; n < 2; ++n) _Pragma("unroll") for (int k = 0; k < 2; ++k) \
;         acc[ai][bj][m][n] = __builtin_amdgcn_mfma_f32_16x16x32_bf16(Bt[n][k], At[m][k], acc[ai][bj][m][n], 0, 0, 0); __builtin_amdgcn_s_setprio(0); } while (0)
; #define PG8_WAIT_V(n) asm volatile("s_waitcnt vmcnt(" #n ")" ::: "memory")
; #define PG8_WAIT_L(n) asm volatile("s_waitcnt lgkmcnt(" #n ")" ::: "memory")
; #define PG8_BAR __builtin_amdgcn_s_barrier()
; #define PG8_SCHED __builtin_amdgcn_sched_barrier(0)
; template <class Epi, class Sched>
; __device__ __forceinline__ void gemm_phase(LAS unsigned char* lds, const Gemm g, const Sched& S, const Epi& E) {
;     ...
;             PG8_BAR; PG8_WAIT_L(0); PG8_MMA(1, 0, At, B0); PG8_BAR; PG8_SCHED;
;             PG8_STAGE(PG8_SB(1, 1), b3 + hstepB, voffB);
;             PG8_WAIT_V(6); PG8_BAR; PG8_MMA(1, 1, At, B1); PG8_BAR;
;         }
;         if constexpr (!Epi::AFTER_DRAIN) E(acc, cur, wr, wc, fr, fq);
;         if (!has_next) break;
; #pragma unroll
;         for (int a = 0; a < 2; ++a)
; #pragma unroll
;             for (int b = 0; b < 2; ++b)
; #pragma unroll
;                 for (int m = 0; m < 4; ++m)
; #pragma unroll
;                     for (int n = 0; n < 2; ++n) acc[a][b][m][n] = (f32x4){0.f, 0.f, 0.f, 0.f};
;         cur = nxt; cA = nA; cB = nB; ++ui;
;     }
	s_waitcnt lgkmcnt(0)
	s_waitcnt lgkmcnt(0)
	v_mfma_f32_16x16x32_bf16 v[60:63], v[146:149], v[162:165], v[60:63]
	v_mfma_f32_16x16x32_bf16 v[56:59], v[154:157], v[162:165], v[56:59]
	v_mfma_f32_16x16x32_bf16 v[44:47], v[146:149], v[170:173], v[44:47]
	v_mfma_f32_16x16x32_bf16 v[40:43], v[154:157], v[170:173], v[40:43]
	v_mfma_f32_16x16x32_bf16 v[28:31], v[146:149], v[190:193], v[28:31]
	v_mfma_f32_16x16x32_bf16 v[24:27], v[154:157], v[190:193], v[24:27]
	v_mfma_f32_16x16x32_bf16 v[16:19], v[146:149], v[202:205], v[16:19]
	v_mfma_f32_16x16x32_bf16 v[8:11], v[154:157], v[202:205], v[8:11]
	v_mfma_f32_16x16x32_bf16 v[60:63], v[150:153], v[166:169], v[60:63]
	v_mfma_f32_16x16x32_bf16 v[56:59], v[158:161], v[166:169], v[56:59]
	v_mfma_f32_16x16x32_bf16 v[44:47], v[150:153], v[174:177], v[44:47]
	v_mfma_f32_16x16x32_bf16 v[40:43], v[158:161], v[174:177], v[40:43]
	v_mfma_f32_16x16x32_bf16 v[28:31], v[150:153], v[198:201], v[28:31]
	v_mfma_f32_16x16x32_bf16 v[24:27], v[158:161], v[198:201], v[24:27]
	v_mfma_f32_16x16x32_bf16 v[16:19], v[150:153], v[206:209], v[16:19]
	v_mfma_f32_16x16x32_bf16 v[8:11], v[158:161], v[206:209], v[8:11]
	s_barrier
	s_add_u32 s24, s24, 0x160080
	s_addc_u32 s25, s25, 0
	s_add_i32 s26, s26, s23
	v_lshl_add_u64 v[146:147], s[24:25], 0, v[128:129]
	s_mov_b32 m0, s26
	s_nop 0
	global_load_lds_dwordx4 v[146:147], off
	v_lshl_add_u64 v[146:147], s[24:25], 0, v[130:131]
	s_add_i32 m0, s26, 0x2000
	s_nop 0
	global_load_lds_dwordx4 v[146:147], off
	s_waitcnt vmcnt(6)
	s_barrier
	v_mfma_f32_16x16x32_bf16 v[52:55], v[210:213], v[162:165], v[52:55]
	v_mfma_f32_16x16x32_bf16 v[48:51], v[218:221], v[162:165], v[48:51]
	v_mfma_f32_16x16x32_bf16 v[36:39], v[210:213], v[170:173], v[36:39]
	v_mfma_f32_16x16x32_bf16 v[32:35], v[218:221], v[170:173], v[32:35]
	v_mfma_f32_16x16x32_bf16 v[20:23], v[210:213], v[190:193], v[20:23]
	v_mfma_f32_16x16x32_bf16 v[12:15], v[218:221], v[190:193], v[12:15]
	v_mfma_f32_16x16x32_bf16 v[4:7], v[210:213], v[202:205], v[4:7]
	v_mfma_f32_16x16x32_bf16 v[0:3], v[218:221], v[202:205], v[0:3]
	v_mfma_f32_16x16x32_bf16 v[52:55], v[214:217], v[166:169], v[52:55]
	v_mfma_f32_16x16x32_bf16 v[48:51], v[222:225], v[166:169], v[48:51]
	v_mfma_f32_16x16x32_bf16 v[36:39], v[214:217], v[174:177], v[36:39]
	v_mfma_f32_16x16x32_bf16 v[32:35], v[222:225], v[174:177], v[32:35]
	v_mfma_f32_16x16x32_bf16 v[20:23], v[214:217], v[198:201], v[20:23]
	v_mfma_f32_16x16x32_bf16 v[12:15], v[222:225], v[198:201], v[12:15]
	v_mfma_f32_16x16x32_bf16 v[4:7], v[214:217], v[206:209], v[4:7]
	v_mfma_f32_16x16x32_bf16 v[0:3], v[222:225], v[206:209], v[0:3]
	s_add_i32 s17, s17, 2
	s_add_u32 s20, s20, 0x100
	s_addc_u32 s21, s21, 0
	s_cmpk_gt_u32 s17, 0x55
	s_barrier
	s_cbranch_scc0 .LBB0_1317
	s_setprio 0
	s_add_u32 s20, s4, 0xffffff00
	s_addc_u32 s21, s5, -1
	s_and_b64 vcc, exec, s[6:7]
	s_cbranch_vccnz .LBB0_1304
	v_mov_b32_e32 v0, 0
	s_mov_b32 s38, s42
	s_mov_b32 s14, s43
	s_mov_b64 s[10:11], s[18:19]
	s_mov_b32 s39, s16
	v_mov_b32_e32 v1, v0
	v_mov_b32_e32 v2, v0
	v_mov_b32_e32 v3, v0
	v_mov_b32_e32 v4, v0
	v_mov_b32_e32 v5, v0
	v_mov_b32_e32 v6, v0
	v_mov_b32_e32 v7, v0
	v_mov_b32_e32 v12, v0
	v_mov_b32_e32 v13, v0
	v_mov_b32_e32 v14, v0
	v_mov_b32_e32 v15, v0
	v_mov_b32_e32 v20, v0
	v_mov_b32_e32 v21, v0
	v_mov_b32_e32 v22, v0
	v_mov_b32_e32 v23, v0
	v_mov_b32_e32 v32, v0
	v_mov_b32_e32 v33, v0
	v_mov_b32_e32 v34, v0
	v_mov_b32_e32 v35, v0
	v_mov_b32_e32 v36, v0
	v_mov_b32_e32 v37, v0
	v_mov_b32_e32 v38, v0
	v_mov_b32_e32 v39, v0
	v_mov_b32_e32 v48, v0
	v_mov_b32_e32 v49, v0
	v_mov_b32_e32 v50, v0
	v_mov_b32_e32 v51, v0
	v_mov_b32_e32 v52, v0
	v_mov_b32_e32 v53, v0
	v_mov_b32_e32 v54, v0
	v_mov_b32_e32 v55, v0
	v_mov_b32_e32 v8, v0
	v_mov_b32_e32 v9, v0
	v_mov_b32_e32 v10, v0
	v_mov_b32_e32 v11, v0
	v_mov_b32_e32 v16, v0
	v_mov_b32_e32 v17, v0
	v_mov_b32_e32 v18, v0
	v_mov_b32_e32 v19, v0
	v_mov_b32_e32 v24, v0
	v_mov_b32_e32 v25, v0
	v_mov_b32_e32 v26, v0
	v_mov_b32_e32 v27, v0
	v_mov_b32_e32 v28, v0
	v_mov_b32_e32 v29, v0
	v_mov_b32_e32 v30, v0
	v_mov_b32_e32 v31, v0
	v_mov_b32_e32 v40, v0
	v_mov_b32_e32 v41, v0
	v_mov_b32_e32 v42, v0
	v_mov_b32_e32 v43, v0
	v_mov_b32_e32 v44, v0
	v_mov_b32_e32 v45, v0
	v_mov_b32_e32 v46, v0
	v_mov_b32_e32 v47, v0
	v_mov_b32_e32 v56, v0
	v_mov_b32_e32 v57, v0
	v_mov_b32_e32 v58, v0
	v_mov_b32_e32 v59, v0
	v_mov_b32_e32 v60, v0
	v_mov_b32_e32 v61, v0
	v_mov_b32_e32 v62, v0
	v_mov_b32_e32 v63, v0
	v_mov_b32_e32 v64, v0
	v_mov_b32_e32 v65, v0
	v_mov_b32_e32 v66, v0
	v_mov_b32_e32 v67, v0
	v_mov_b32_e32 v68, v0
	v_mov_b32_e32 v69, v0
	v_mov_b32_e32 v70, v0
	v_mov_b32_e32 v71, v0
	v_mov_b32_e32 v80, v0
	v_mov_b32_e32 v81, v0
	v_mov_b32_e32 v82, v0
	v_mov_b32_e32 v83, v0
	v_mov_b32_e32 v84, v0
	v_mov_b32_e32 v85, v0
	v_mov_b32_e32 v86, v0
	v_mov_b32_e32 v87, v0
	v_mov_b32_e32 v96, v0
	v_mov_b32_e32 v97, v0
	v_mov_b32_e32 v98, v0
	v_mov_b32_e32 v99, v0
	v_mov_b32_e32 v100, v0
	v_mov_b32_e32 v101, v0
	v_mov_b32_e32 v102, v0
	v_mov_b32_e32 v103, v0
	v_mov_b32_e32 v112, v0
	v_mov_b32_e32 v113, v0
	v_mov_b32_e32 v114, v0
	v_mov_b32_e32 v115, v0
	v_mov_b32_e32 v116, v0
	v_mov_b32_e32 v117, v0
	v_mov_b32_e32 v118, v0
	v_mov_b32_e32 v119, v0
	v_mov_b32_e32 v72, v0
	v_mov_b32_e32 v73, v0
	v_mov_b32_e32 v74, v0
	v_mov_b32_e32 v75, v0
	v_mov_b32_e32 v76, v0
	v_mov_b32_e32 v77, v0
	v_mov_b32_e32 v78, v0
	v_mov_b32_e32 v79, v0
	v_mov_b32_e32 v88, v0
	v_mov_b32_e32 v89, v0
	v_mov_b32_e32 v90, v0
	v_mov_b32_e32 v91, v0
	v_mov_b32_e32 v92, v0
	v_mov_b32_e32 v93, v0
	v_mov_b32_e32 v94, v0
	v_mov_b32_e32 v95, v0
	v_mov_b32_e32 v104, v0
	v_mov_b32_e32 v105, v0
	v_mov_b32_e32 v106, v0
	v_mov_b32_e32 v107, v0
	v_mov_b32_e32 v108, v0
	v_mov_b32_e32 v109, v0
	v_mov_b32_e32 v110, v0
	v_mov_b32_e32 v111, v0
	v_mov_b32_e32 v120, v0
	v_mov_b32_e32 v121, v0
	v_mov_b32_e32 v122, v0
	v_mov_b32_e32 v123, v0
	v_mov_b32_e32 v124, v0
	v_mov_b32_e32 v125, v0
	v_mov_b32_e32 v126, v0
	v_mov_b32_e32 v127, v0
	s_andn2_b64 vcc, exec, s[0:1]
	s_cbranch_vccnz .LBB0_1305
